# conv_item halo: 30 serialized conditional load+sigmoid blocks replaced by one path with all 60 loads in flight (on v22)
# baseline (speedup 1.0000x reference)
.LBB0_837:
	s_add_i32 s6, s61, s60
	s_load_dwordx2 s[54:55], s[0:1], 0xf8
	s_waitcnt lgkmcnt(0)
	s_ashr_i32 s6, s6, 6
	s_load_dwordx2 s[52:53], s[0:1], 0x100
	s_waitcnt lgkmcnt(0)
	s_load_dwordx2 s[56:57], s[0:1], 0x108
	s_waitcnt lgkmcnt(0)
	s_ashr_i32 s7, s6, 31
	s_and_b32 s91, s90, 0x7e0
	s_load_dwordx2 s[50:51], s[0:1], 0x110
	s_waitcnt lgkmcnt(0)
	s_lshl_b64 s[44:45], s[6:7], 11
	s_cmp_lg_u32 s91, 0
	v_mov_b32_e32 v100, 0
	s_cselect_b64 s[58:59], -1, 0
	s_cmp_eq_u32 s91, 0
	v_mov_b32_e32 v105, 0
	v_cndmask_b32_e64 v0, 0, 1, s[58:59]
	v_cmp_ne_u32_e64 s[40:41], 1, v0
	v_mov_b32_e32 v105, 0
	v_mov_b32_e32 v100, 0
	v_mov_b32_e32 v104, 0
	v_mov_b32_e32 v98, 0
	v_mov_b32_e32 v103, 0
	v_mov_b32_e32 v96, 0
	v_mov_b32_e32 v102, 0
	v_mov_b32_e32 v94, 0
	v_mov_b32_e32 v101, 0
	v_mov_b32_e32 v92, 0
	v_mov_b32_e32 v99, 0
	v_mov_b32_e32 v90, 0
	v_mov_b32_e32 v97, 0
	v_mov_b32_e32 v88, 0
	v_mov_b32_e32 v95, 0
	v_mov_b32_e32 v86, 0
	v_mov_b32_e32 v93, 0
	v_mov_b32_e32 v84, 0
	v_mov_b32_e32 v91, 0
	v_mov_b32_e32 v82, 0
	v_mov_b32_e32 v89, 0
	v_mov_b32_e32 v80, 0
	v_mov_b32_e32 v87, 0
	v_mov_b32_e32 v79, 0
	v_mov_b32_e32 v85, 0
	v_mov_b32_e32 v78, 0
	v_mov_b32_e32 v83, 0
	v_mov_b32_e32 v77, 0
	v_mov_b32_e32 v81, 0
	v_mov_b32_e32 v48, 0
	s_cmp_eq_u32 s91, 0
	s_cbranch_scc1 .Lconv_halo_done
	s_sub_i32 s6, s91, 30
	s_add_u32 s6, s44, s6
	s_addc_u32 s7, s45, 0
	s_mul_i32 s8, s7, 0xc00
	v_mad_u64_u32 v[114:115], s[6:7], s6, v211, v[16:17]
	v_add_u32_e32 v115, s8, v115
	s_mov_b64 s[6:7], 0xc00
	global_load_ushort v116, v[114:115], off offset:1856
	global_load_ushort v147, v[114:115], off offset:832
	v_lshl_add_u64 v[114:115], v[114:115], 0, s[6:7]
	global_load_ushort v117, v[114:115], off offset:1856
	global_load_ushort v148, v[114:115], off offset:832
	v_lshl_add_u64 v[114:115], v[114:115], 0, s[6:7]
	global_load_ushort v118, v[114:115], off offset:1856
	global_load_ushort v149, v[114:115], off offset:832
	v_lshl_add_u64 v[114:115], v[114:115], 0, s[6:7]
	global_load_ushort v119, v[114:115], off offset:1856
	global_load_ushort v150, v[114:115], off offset:832
	v_lshl_add_u64 v[114:115], v[114:115], 0, s[6:7]
	global_load_ushort v120, v[114:115], off offset:1856
	global_load_ushort v151, v[114:115], off offset:832
	v_lshl_add_u64 v[114:115], v[114:115], 0, s[6:7]
	global_load_ushort v121, v[114:115], off offset:1856
	global_load_ushort v152, v[114:115], off offset:832
	v_lshl_add_u64 v[114:115], v[114:115], 0, s[6:7]
	global_load_ushort v122, v[114:115], off offset:1856
	global_load_ushort v153, v[114:115], off offset:832
	v_lshl_add_u64 v[114:115], v[114:115], 0, s[6:7]
	global_load_ushort v123, v[114:115], off offset:1856
	global_load_ushort v156, v[114:115], off offset:832
	v_lshl_add_u64 v[114:115], v[114:115], 0, s[6:7]
	global_load_ushort v124, v[114:115], off offset:1856
	global_load_ushort v157, v[114:115], off offset:832
	v_lshl_add_u64 v[114:115], v[114:115], 0, s[6:7]
	global_load_ushort v125, v[114:115], off offset:1856
	global_load_ushort v158, v[114:115], off offset:832
	v_lshl_add_u64 v[114:115], v[114:115], 0, s[6:7]
	global_load_ushort v126, v[114:115], off offset:1856
	global_load_ushort v159, v[114:115], off offset:832
	v_lshl_add_u64 v[114:115], v[114:115], 0, s[6:7]
	global_load_ushort v127, v[114:115], off offset:1856
	global_load_ushort v160, v[114:115], off offset:832
	v_lshl_add_u64 v[114:115], v[114:115], 0, s[6:7]
	global_load_ushort v128, v[114:115], off offset:1856
	global_load_ushort v161, v[114:115], off offset:832
	v_lshl_add_u64 v[114:115], v[114:115], 0, s[6:7]
	global_load_ushort v129, v[114:115], off offset:1856
	global_load_ushort v162, v[114:115], off offset:832
	v_lshl_add_u64 v[114:115], v[114:115], 0, s[6:7]
	global_load_ushort v131, v[114:115], off offset:1856
	global_load_ushort v163, v[114:115], off offset:832
	v_lshl_add_u64 v[114:115], v[114:115], 0, s[6:7]
	global_load_ushort v132, v[114:115], off offset:1856
	global_load_ushort v164, v[114:115], off offset:832
	v_lshl_add_u64 v[114:115], v[114:115], 0, s[6:7]
	global_load_ushort v133, v[114:115], off offset:1856
	global_load_ushort v165, v[114:115], off offset:832
	v_lshl_add_u64 v[114:115], v[114:115], 0, s[6:7]
	global_load_ushort v134, v[114:115], off offset:1856
	global_load_ushort v166, v[114:115], off offset:832
	v_lshl_add_u64 v[114:115], v[114:115], 0, s[6:7]
	global_load_ushort v135, v[114:115], off offset:1856
	global_load_ushort v167, v[114:115], off offset:832
	v_lshl_add_u64 v[114:115], v[114:115], 0, s[6:7]
	global_load_ushort v136, v[114:115], off offset:1856
	global_load_ushort v168, v[114:115], off offset:832
	v_lshl_add_u64 v[114:115], v[114:115], 0, s[6:7]
	global_load_ushort v137, v[114:115], off offset:1856
	global_load_ushort v169, v[114:115], off offset:832
	v_lshl_add_u64 v[114:115], v[114:115], 0, s[6:7]
	global_load_ushort v138, v[114:115], off offset:1856
	global_load_ushort v170, v[114:115], off offset:832
	v_lshl_add_u64 v[114:115], v[114:115], 0, s[6:7]
	global_load_ushort v139, v[114:115], off offset:1856
	global_load_ushort v171, v[114:115], off offset:832
	v_lshl_add_u64 v[114:115], v[114:115], 0, s[6:7]
	global_load_ushort v140, v[114:115], off offset:1856
	global_load_ushort v172, v[114:115], off offset:832
	v_lshl_add_u64 v[114:115], v[114:115], 0, s[6:7]
	global_load_ushort v141, v[114:115], off offset:1856
	global_load_ushort v173, v[114:115], off offset:832
	v_lshl_add_u64 v[114:115], v[114:115], 0, s[6:7]
	global_load_ushort v142, v[114:115], off offset:1856
	global_load_ushort v174, v[114:115], off offset:832
	v_lshl_add_u64 v[114:115], v[114:115], 0, s[6:7]
	global_load_ushort v143, v[114:115], off offset:1856
	global_load_ushort v175, v[114:115], off offset:832
	v_lshl_add_u64 v[114:115], v[114:115], 0, s[6:7]
	global_load_ushort v144, v[114:115], off offset:1856
	global_load_ushort v176, v[114:115], off offset:832
	v_lshl_add_u64 v[114:115], v[114:115], 0, s[6:7]
	global_load_ushort v145, v[114:115], off offset:1856
	global_load_ushort v178, v[114:115], off offset:832
	v_lshl_add_u64 v[114:115], v[114:115], 0, s[6:7]
	global_load_ushort v146, v[114:115], off offset:1856
	global_load_ushort v179, v[114:115], off offset:832
	s_waitcnt vmcnt(58)
	v_lshlrev_b32_e32 v1, 16, v116
	v_mul_f32_e32 v1, 0xbfb8aa3b, v1
	v_exp_f32_e32 v1, v1
	v_lshlrev_b32_e32 v0, 16, v147
	v_add_f32_e32 v1, 1.0, v1
	v_rcp_f32_e32 v1, v1
	s_nop 0
	v_mul_f32_e32 v105, v1, v0
	s_waitcnt vmcnt(56)
	v_lshlrev_b32_e32 v1, 16, v117
	v_mul_f32_e32 v1, 0xbfb8aa3b, v1
	v_exp_f32_e32 v1, v1
	v_lshlrev_b32_e32 v0, 16, v148
	v_add_f32_e32 v1, 1.0, v1
	v_rcp_f32_e32 v1, v1
	s_nop 0
	v_mul_f32_e32 v100, v1, v0
	s_waitcnt vmcnt(54)
	v_lshlrev_b32_e32 v1, 16, v118
	v_mul_f32_e32 v1, 0xbfb8aa3b, v1
	v_exp_f32_e32 v1, v1
	v_lshlrev_b32_e32 v0, 16, v149
	v_add_f32_e32 v1, 1.0, v1
	v_rcp_f32_e32 v1, v1
	s_nop 0
	v_mul_f32_e32 v104, v1, v0
	s_waitcnt vmcnt(52)
	v_lshlrev_b32_e32 v1, 16, v119
	v_mul_f32_e32 v1, 0xbfb8aa3b, v1
	v_exp_f32_e32 v1, v1
	v_lshlrev_b32_e32 v0, 16, v150
	v_add_f32_e32 v1, 1.0, v1
	v_rcp_f32_e32 v1, v1
	s_nop 0
	v_mul_f32_e32 v98, v1, v0
	s_waitcnt vmcnt(50)
	v_lshlrev_b32_e32 v1, 16, v120
	v_mul_f32_e32 v1, 0xbfb8aa3b, v1
	v_exp_f32_e32 v1, v1
	v_lshlrev_b32_e32 v0, 16, v151
	v_add_f32_e32 v1, 1.0, v1
	v_rcp_f32_e32 v1, v1
	s_nop 0
	v_mul_f32_e32 v103, v1, v0
	s_waitcnt vmcnt(48)
	v_lshlrev_b32_e32 v1, 16, v121
	v_mul_f32_e32 v1, 0xbfb8aa3b, v1
	v_exp_f32_e32 v1, v1
	v_lshlrev_b32_e32 v0, 16, v152
	v_add_f32_e32 v1, 1.0, v1
	v_rcp_f32_e32 v1, v1
	s_nop 0
	v_mul_f32_e32 v96, v1, v0
	s_waitcnt vmcnt(46)
	v_lshlrev_b32_e32 v1, 16, v122
	v_mul_f32_e32 v1, 0xbfb8aa3b, v1
	v_exp_f32_e32 v1, v1
	v_lshlrev_b32_e32 v0, 16, v153
	v_add_f32_e32 v1, 1.0, v1
	v_rcp_f32_e32 v1, v1
	s_nop 0
	v_mul_f32_e32 v102, v1, v0
	s_waitcnt vmcnt(44)
	v_lshlrev_b32_e32 v1, 16, v123
	v_mul_f32_e32 v1, 0xbfb8aa3b, v1
	v_exp_f32_e32 v1, v1
	v_lshlrev_b32_e32 v0, 16, v156
	v_add_f32_e32 v1, 1.0, v1
	v_rcp_f32_e32 v1, v1
	s_nop 0
	v_mul_f32_e32 v94, v1, v0
	s_waitcnt vmcnt(42)
	v_lshlrev_b32_e32 v1, 16, v124
	v_mul_f32_e32 v1, 0xbfb8aa3b, v1
	v_exp_f32_e32 v1, v1
	v_lshlrev_b32_e32 v0, 16, v157
	v_add_f32_e32 v1, 1.0, v1
	v_rcp_f32_e32 v1, v1
	s_nop 0
	v_mul_f32_e32 v101, v1, v0
	s_waitcnt vmcnt(40)
	v_lshlrev_b32_e32 v1, 16, v125
	v_mul_f32_e32 v1, 0xbfb8aa3b, v1
	v_exp_f32_e32 v1, v1
	v_lshlrev_b32_e32 v0, 16, v158
	v_add_f32_e32 v1, 1.0, v1
	v_rcp_f32_e32 v1, v1
	s_nop 0
	v_mul_f32_e32 v92, v1, v0
	s_waitcnt vmcnt(38)
	v_lshlrev_b32_e32 v1, 16, v126
	v_mul_f32_e32 v1, 0xbfb8aa3b, v1
	v_exp_f32_e32 v1, v1
	v_lshlrev_b32_e32 v0, 16, v159
	v_add_f32_e32 v1, 1.0, v1
	v_rcp_f32_e32 v1, v1
	s_nop 0
	v_mul_f32_e32 v99, v1, v0
	s_waitcnt vmcnt(36)
	v_lshlrev_b32_e32 v1, 16, v127
	v_mul_f32_e32 v1, 0xbfb8aa3b, v1
	v_exp_f32_e32 v1, v1
	v_lshlrev_b32_e32 v0, 16, v160
	v_add_f32_e32 v1, 1.0, v1
	v_rcp_f32_e32 v1, v1
	s_nop 0
	v_mul_f32_e32 v90, v1, v0
	s_waitcnt vmcnt(34)
	v_lshlrev_b32_e32 v1, 16, v128
	v_mul_f32_e32 v1, 0xbfb8aa3b, v1
	v_exp_f32_e32 v1, v1
	v_lshlrev_b32_e32 v0, 16, v161
	v_add_f32_e32 v1, 1.0, v1
	v_rcp_f32_e32 v1, v1
	s_nop 0
	v_mul_f32_e32 v97, v1, v0
	s_waitcnt vmcnt(32)
	v_lshlrev_b32_e32 v1, 16, v129
	v_mul_f32_e32 v1, 0xbfb8aa3b, v1
	v_exp_f32_e32 v1, v1
	v_lshlrev_b32_e32 v0, 16, v162
	v_add_f32_e32 v1, 1.0, v1
	v_rcp_f32_e32 v1, v1
	s_nop 0
	v_mul_f32_e32 v88, v1, v0
	s_waitcnt vmcnt(30)
	v_lshlrev_b32_e32 v1, 16, v131
	v_mul_f32_e32 v1, 0xbfb8aa3b, v1
	v_exp_f32_e32 v1, v1
	v_lshlrev_b32_e32 v0, 16, v163
	v_add_f32_e32 v1, 1.0, v1
	v_rcp_f32_e32 v1, v1
	s_nop 0
	v_mul_f32_e32 v95, v1, v0
	s_waitcnt vmcnt(28)
	v_lshlrev_b32_e32 v1, 16, v132
	v_mul_f32_e32 v1, 0xbfb8aa3b, v1
	v_exp_f32_e32 v1, v1
	v_lshlrev_b32_e32 v0, 16, v164
	v_add_f32_e32 v1, 1.0, v1
	v_rcp_f32_e32 v1, v1
	s_nop 0
	v_mul_f32_e32 v86, v1, v0
	s_waitcnt vmcnt(26)
	v_lshlrev_b32_e32 v1, 16, v133
	v_mul_f32_e32 v1, 0xbfb8aa3b, v1
	v_exp_f32_e32 v1, v1
	v_lshlrev_b32_e32 v0, 16, v165
	v_add_f32_e32 v1, 1.0, v1
	v_rcp_f32_e32 v1, v1
	s_nop 0
	v_mul_f32_e32 v93, v1, v0
	s_waitcnt vmcnt(24)
	v_lshlrev_b32_e32 v1, 16, v134
	v_mul_f32_e32 v1, 0xbfb8aa3b, v1
	v_exp_f32_e32 v1, v1
	v_lshlrev_b32_e32 v0, 16, v166
	v_add_f32_e32 v1, 1.0, v1
	v_rcp_f32_e32 v1, v1
	s_nop 0
	v_mul_f32_e32 v84, v1, v0
	s_waitcnt vmcnt(22)
	v_lshlrev_b32_e32 v1, 16, v135
	v_mul_f32_e32 v1, 0xbfb8aa3b, v1
	v_exp_f32_e32 v1, v1
	v_lshlrev_b32_e32 v0, 16, v167
	v_add_f32_e32 v1, 1.0, v1
	v_rcp_f32_e32 v1, v1
	s_nop 0
	v_mul_f32_e32 v91, v1, v0
	s_waitcnt vmcnt(20)
	v_lshlrev_b32_e32 v1, 16, v136
	v_mul_f32_e32 v1, 0xbfb8aa3b, v1
	v_exp_f32_e32 v1, v1
	v_lshlrev_b32_e32 v0, 16, v168
	v_add_f32_e32 v1, 1.0, v1
	v_rcp_f32_e32 v1, v1
	s_nop 0
	v_mul_f32_e32 v82, v1, v0
	s_waitcnt vmcnt(18)
	v_lshlrev_b32_e32 v1, 16, v137
	v_mul_f32_e32 v1, 0xbfb8aa3b, v1
	v_exp_f32_e32 v1, v1
	v_lshlrev_b32_e32 v0, 16, v169
	v_add_f32_e32 v1, 1.0, v1
	v_rcp_f32_e32 v1, v1
	s_nop 0
	v_mul_f32_e32 v89, v1, v0
	s_waitcnt vmcnt(16)
	v_lshlrev_b32_e32 v1, 16, v138
	v_mul_f32_e32 v1, 0xbfb8aa3b, v1
	v_exp_f32_e32 v1, v1
	v_lshlrev_b32_e32 v0, 16, v170
	v_add_f32_e32 v1, 1.0, v1
	v_rcp_f32_e32 v1, v1
	s_nop 0
	v_mul_f32_e32 v80, v1, v0
	s_waitcnt vmcnt(14)
	v_lshlrev_b32_e32 v1, 16, v139
	v_mul_f32_e32 v1, 0xbfb8aa3b, v1
	v_exp_f32_e32 v1, v1
	v_lshlrev_b32_e32 v0, 16, v171
	v_add_f32_e32 v1, 1.0, v1
	v_rcp_f32_e32 v1, v1
	s_nop 0
	v_mul_f32_e32 v87, v1, v0
	s_waitcnt vmcnt(12)
	v_lshlrev_b32_e32 v1, 16, v140
	v_mul_f32_e32 v1, 0xbfb8aa3b, v1
	v_exp_f32_e32 v1, v1
	v_lshlrev_b32_e32 v0, 16, v172
	v_add_f32_e32 v1, 1.0, v1
	v_rcp_f32_e32 v1, v1
	s_nop 0
	v_mul_f32_e32 v79, v1, v0
	s_waitcnt vmcnt(10)
	v_lshlrev_b32_e32 v1, 16, v141
	v_mul_f32_e32 v1, 0xbfb8aa3b, v1
	v_exp_f32_e32 v1, v1
	v_lshlrev_b32_e32 v0, 16, v173
	v_add_f32_e32 v1, 1.0, v1
	v_rcp_f32_e32 v1, v1
	s_nop 0
	v_mul_f32_e32 v85, v1, v0
	s_waitcnt vmcnt(8)
	v_lshlrev_b32_e32 v1, 16, v142
	v_mul_f32_e32 v1, 0xbfb8aa3b, v1
	v_exp_f32_e32 v1, v1
	v_lshlrev_b32_e32 v0, 16, v174
	v_add_f32_e32 v1, 1.0, v1
	v_rcp_f32_e32 v1, v1
	s_nop 0
	v_mul_f32_e32 v78, v1, v0
	s_waitcnt vmcnt(6)
	v_lshlrev_b32_e32 v1, 16, v143
	v_mul_f32_e32 v1, 0xbfb8aa3b, v1
	v_exp_f32_e32 v1, v1
	v_lshlrev_b32_e32 v0, 16, v175
	v_add_f32_e32 v1, 1.0, v1
	v_rcp_f32_e32 v1, v1
	s_nop 0
	v_mul_f32_e32 v83, v1, v0
	s_waitcnt vmcnt(4)
	v_lshlrev_b32_e32 v1, 16, v144
	v_mul_f32_e32 v1, 0xbfb8aa3b, v1
	v_exp_f32_e32 v1, v1
	v_lshlrev_b32_e32 v0, 16, v176
	v_add_f32_e32 v1, 1.0, v1
	v_rcp_f32_e32 v1, v1
	s_nop 0
	v_mul_f32_e32 v77, v1, v0
	s_waitcnt vmcnt(2)
	v_lshlrev_b32_e32 v1, 16, v145
	v_mul_f32_e32 v1, 0xbfb8aa3b, v1
	v_exp_f32_e32 v1, v1
	v_lshlrev_b32_e32 v0, 16, v178
	v_add_f32_e32 v1, 1.0, v1
	v_rcp_f32_e32 v1, v1
	s_nop 0
	v_mul_f32_e32 v81, v1, v0
	s_waitcnt vmcnt(0)
	v_lshlrev_b32_e32 v1, 16, v146
	v_mul_f32_e32 v1, 0xbfb8aa3b, v1
	v_exp_f32_e32 v1, v1
	v_lshlrev_b32_e32 v0, 16, v179
	v_add_f32_e32 v1, 1.0, v1
	v_rcp_f32_e32 v1, v1
	s_nop 0
	v_mul_f32_e32 v48, v1, v0
.Lconv_halo_done:
	s_branch .LBB0_836
.LBB0_897:
	s_mov_b64 s[40:41], 0
